# select_query: next query's score row prefetched into spare VGPRs while the current query is selected
# baseline (speedup 1.0000x reference)
.LBB0_721:
	s_cmp_lt_u32 s28, 8
	s_cbranch_scc0 .Lselb_entry
	s_add_i32 s0, s28, s13
	s_add_i32 s4, s28, s89
	s_ashr_i32 s1, s0, 31
	s_add_i32 s2, s4, 0x100
	s_lshl_b64 s[0:1], s[0:1], 13
	s_ashr_i32 s5, s2, 8
	s_cmp_gt_i32 s5, 0
	s_cselect_b64 s[2:3], -1, 0
	s_waitcnt vmcnt(1)
	v_lshl_add_u64 v[34:35], v[84:85], 0, s[0:1]
	v_mov_b32_e32 v26, 0
	s_and_b64 vcc, exec, s[2:3]
	v_mov_b32_e32 v30, 0
	v_mov_b32_e32 v31, 0
	v_mov_b32_e32 v32, 0
	v_mov_b32_e32 v33, 0
	s_cbranch_vccz .LBB0_723
	global_load_dwordx4 v[30:33], v[34:35], off

.LBB0_735:
	s_cmp_gt_i32 s5, 7
	s_cselect_b64 s[0:1], -1, 0
	s_cmp_lt_i32 s5, 8
	v_mov_b32_e32 v3, 0
	v_mov_b32_e32 v4, 0
	v_mov_b32_e32 v5, 0
	s_cbranch_scc1 .LBB0_737
	v_add_co_u32_e32 v2, vcc, 0x1000, v34
	s_nop 1
	v_addc_co_u32_e32 v3, vcc, 0, v35, vcc
	global_load_dwordx4 v[2:5], v[2:3], off offset:3072
	s_branch .LBB0_737
.Lselb_entry:
	s_add_i32 s0, s28, s13
	s_add_i32 s4, s28, s89
	s_ashr_i32 s1, s0, 31
	s_add_i32 s2, s4, 0x100
	s_lshl_b64 s[0:1], s[0:1], 13
	s_ashr_i32 s5, s2, 8
	s_cmp_gt_i32 s5, 0
	s_cselect_b64 s[2:3], -1, 0
	s_waitcnt vmcnt(1)
	v_lshl_add_u64 v[34:35], v[84:85], 0, s[0:1]
	v_mov_b32_e32 v26, 0
	s_and_b64 vcc, exec, s[2:3]
	v_mov_b32_e32 v30, 0
	v_mov_b32_e32 v31, 0
	v_mov_b32_e32 v32, 0
	v_mov_b32_e32 v33, 0
	s_cbranch_vccz .Lselb_723
	v_mov_b64_e32 v[30:31], v[200:201]
	v_mov_b64_e32 v[32:33], v[202:203]
.Lselb_723:
	s_cmp_gt_i32 s5, 1
	s_cselect_b64 s[72:73], -1, 0
	s_cmp_lt_i32 s5, 2
	v_mov_b32_e32 v27, 0
	v_mov_b32_e32 v28, 0
	v_mov_b32_e32 v29, 0
	s_cbranch_scc1 .Lselb_725
	v_mov_b64_e32 v[26:27], v[204:205]
	v_mov_b64_e32 v[28:29], v[206:207]
.Lselb_725:
	s_cmp_gt_i32 s5, 2
	v_mov_b32_e32 v18, 0
	s_cselect_b64 s[74:75], -1, 0
	s_cmp_lt_i32 s5, 3
	v_mov_b32_e32 v22, 0
	v_mov_b32_e32 v23, 0
	v_mov_b32_e32 v24, 0
	v_mov_b32_e32 v25, 0
	s_cbranch_scc1 .Lselb_727
	v_mov_b64_e32 v[22:23], v[208:209]
	v_mov_b64_e32 v[24:25], v[210:211]
.Lselb_727:
	s_cmp_gt_i32 s5, 3
	s_cselect_b64 s[76:77], -1, 0
	s_cmp_lt_i32 s5, 4
	v_mov_b32_e32 v19, 0
	v_mov_b32_e32 v20, 0
	v_mov_b32_e32 v21, 0
	s_cbranch_scc1 .Lselb_729
	v_mov_b64_e32 v[18:19], v[212:213]
	v_mov_b64_e32 v[20:21], v[214:215]
.Lselb_729:
	s_cmp_gt_i32 s5, 4
	v_mov_b32_e32 v10, 0
	s_cselect_b64 s[82:83], -1, 0
	s_cmp_lt_i32 s5, 5
	v_mov_b32_e32 v14, 0
	v_mov_b32_e32 v15, 0
	v_mov_b32_e32 v16, 0
	v_mov_b32_e32 v17, 0
	s_cbranch_scc1 .Lselb_731
	v_add_co_u32_e32 v2, vcc, 0x1000, v34
	s_nop 1
	v_addc_co_u32_e32 v3, vcc, 0, v35, vcc
	v_mov_b64_e32 v[14:15], v[216:217]
	v_mov_b64_e32 v[16:17], v[218:219]
.Lselb_731:
	s_cmp_gt_i32 s5, 5
	s_cselect_b64 s[80:81], -1, 0
	s_cmp_lt_i32 s5, 6
	v_mov_b32_e32 v11, 0
	v_mov_b32_e32 v12, 0
	v_mov_b32_e32 v13, 0
	s_cbranch_scc1 .Lselb_733
	v_add_co_u32_e32 v2, vcc, 0x1000, v34
	s_nop 1
	v_addc_co_u32_e32 v3, vcc, 0, v35, vcc
	v_mov_b64_e32 v[10:11], v[220:221]
	v_mov_b64_e32 v[12:13], v[222:223]
.Lselb_733:
	s_cmp_gt_i32 s5, 6
	v_mov_b32_e32 v2, 0
	s_cselect_b64 s[78:79], -1, 0
	s_cmp_lt_i32 s5, 7
	v_mov_b32_e32 v6, 0
	v_mov_b32_e32 v7, 0
	v_mov_b32_e32 v8, 0
	v_mov_b32_e32 v9, 0
	s_cbranch_scc1 .Lselb_735
	v_add_co_u32_e32 v4, vcc, 0x1000, v34
	s_nop 1
	v_addc_co_u32_e32 v5, vcc, 0, v35, vcc
	v_mov_b64_e32 v[6:7], v[224:225]
	v_mov_b64_e32 v[8:9], v[226:227]
.Lselb_735:
	s_cmp_gt_i32 s5, 7
	s_cselect_b64 s[0:1], -1, 0
	s_cmp_lt_i32 s5, 8
	v_mov_b32_e32 v3, 0
	v_mov_b32_e32 v4, 0
	v_mov_b32_e32 v5, 0
	s_cbranch_scc1 .LBB0_737
	v_add_co_u32_e32 v2, vcc, 0x1000, v34
	s_nop 1
	v_addc_co_u32_e32 v3, vcc, 0, v35, vcc
	v_mov_b64_e32 v[2:3], v[228:229]
	v_mov_b64_e32 v[4:5], v[230:231]
.LBB0_737:
	v_mov_b32_e32 v236, s28
	v_add_u32_e32 v236, s13, v236
	v_add_u32_e32 v236, 8, v236
	v_mov_b32_e32 v237, 0
	v_lshl_or_b32 v238, v236, 1, 1
	v_mov_b32_e32 v239, 0
	v_lshlrev_b64 v[232:233], 13, v[236:237]
	v_lshlrev_b64 v[234:235], 12, v[238:239]
	v_lshl_add_u64 v[232:233], v[84:85], 0, v[232:233]
	v_lshl_add_u64 v[234:235], v[84:85], 0, v[234:235]
	global_load_dwordx4 v[200:203], v[232:233], off
	global_load_dwordx4 v[204:207], v[232:233], off offset:1024
	global_load_dwordx4 v[208:211], v[232:233], off offset:2048
	global_load_dwordx4 v[212:215], v[232:233], off offset:3072
	global_load_dwordx4 v[216:219], v[234:235], off
	global_load_dwordx4 v[220:223], v[234:235], off offset:1024
	global_load_dwordx4 v[224:227], v[234:235], off offset:2048
	global_load_dwordx4 v[228:231], v[234:235], off offset:3072
	v_cmp_ge_i32_e32 vcc, s4, v132
	s_and_b64 s[6:7], s[78:79], vcc
	v_cmp_lt_i32_e32 vcc, s4, v134
	v_cndmask_b32_e64 v1, 0, 1, s[6:7]
	s_nop 0
	v_cndmask_b32_e64 v34, 2, 0, vcc
	v_cmp_lt_i32_e32 vcc, s4, v136
	s_nop 1
	v_cndmask_b32_e64 v35, 4, 0, vcc
	v_cmp_lt_i32_e32 vcc, s4, v138
	v_or_b32_e32 v34, v35, v34
	s_nop 0
	v_cndmask_b32_e64 v36, 8, 0, vcc
	v_cmp_ge_i32_e32 vcc, s4, v124
	s_and_b64 s[6:7], s[80:81], vcc
	v_cmp_lt_i32_e32 vcc, s4, v126
	v_or3_b32 v1, v34, v36, v1
	v_cndmask_b32_e64 v99, 0, v1, s[78:79]
	v_cndmask_b32_e64 v34, 2, 0, vcc
	v_cmp_lt_i32_e32 vcc, s4, v128
	v_cndmask_b32_e64 v1, 0, 1, s[6:7]
	s_nop 0
	v_cndmask_b32_e64 v35, 4, 0, vcc
	v_cmp_lt_i32_e32 vcc, s4, v130
	v_or_b32_e32 v34, v35, v34
	s_nop 0
	v_cndmask_b32_e64 v36, 8, 0, vcc
	v_cmp_ge_i32_e32 vcc, s4, v116
	s_and_b64 s[6:7], s[82:83], vcc
	v_cmp_lt_i32_e32 vcc, s4, v118
	v_or3_b32 v1, v34, v36, v1
	v_cndmask_b32_e64 v107, 0, v1, s[80:81]
	v_cndmask_b32_e64 v34, 2, 0, vcc
	v_cmp_lt_i32_e32 vcc, s4, v120
	v_cndmask_b32_e64 v1, 0, 1, s[6:7]
	s_nop 0
	v_cndmask_b32_e64 v35, 4, 0, vcc
	v_cmp_lt_i32_e32 vcc, s4, v122
	v_or_b32_e32 v34, v35, v34
	s_nop 0
	v_cndmask_b32_e64 v36, 8, 0, vcc
	v_cmp_ge_i32_e32 vcc, s4, v108
	s_and_b64 s[6:7], s[76:77], vcc
	v_cmp_lt_i32_e32 vcc, s4, v110
	v_or3_b32 v1, v34, v36, v1
	v_cndmask_b32_e64 v115, 0, v1, s[82:83]
	v_cndmask_b32_e64 v34, 2, 0, vcc
	v_cmp_lt_i32_e32 vcc, s4, v112
	v_cndmask_b32_e64 v1, 0, 1, s[6:7]
	s_nop 0
	v_cndmask_b32_e64 v35, 4, 0, vcc
	v_cmp_lt_i32_e32 vcc, s4, v114
	v_or_b32_e32 v34, v35, v34
	s_nop 0
	v_cndmask_b32_e64 v36, 8, 0, vcc
	v_cmp_ge_i32_e32 vcc, s4, v100
	s_and_b64 s[6:7], s[74:75], vcc
	v_cmp_lt_i32_e32 vcc, s4, v102
	v_or3_b32 v1, v34, v36, v1
	v_cndmask_b32_e64 v123, 0, v1, s[76:77]
	v_cndmask_b32_e64 v34, 2, 0, vcc
	v_cmp_lt_i32_e32 vcc, s4, v104
	v_cndmask_b32_e64 v1, 0, 1, s[6:7]
	s_nop 0
	v_cndmask_b32_e64 v35, 4, 0, vcc
	v_cmp_lt_i32_e32 vcc, s4, v106
	v_or_b32_e32 v34, v35, v34
	s_nop 0
	v_cndmask_b32_e64 v36, 8, 0, vcc
	v_cmp_ge_i32_e32 vcc, s4, v92
	s_and_b64 s[6:7], s[72:73], vcc
	v_cmp_lt_i32_e32 vcc, s4, v94
	v_or3_b32 v1, v34, v36, v1
	v_cndmask_b32_e64 v131, 0, v1, s[74:75]
	v_cndmask_b32_e64 v34, 2, 0, vcc
	v_cmp_lt_i32_e32 vcc, s4, v96
	v_cndmask_b32_e64 v1, 0, 1, s[6:7]
	s_nop 0
	v_cndmask_b32_e64 v35, 4, 0, vcc
	v_cmp_lt_i32_e32 vcc, s4, v98
	v_or_b32_e32 v34, v35, v34
	s_nop 0
	v_cndmask_b32_e64 v36, 8, 0, vcc
	v_cmp_ge_i32_e32 vcc, s4, v82
	s_and_b64 s[6:7], s[2:3], vcc
	v_cmp_gt_i32_e32 vcc, s4, v82
	v_or3_b32 v1, v34, v36, v1
	v_cndmask_b32_e64 v139, 0, v1, s[72:73]
	v_cndmask_b32_e64 v34, 0, 2, vcc
	v_cmp_lt_i32_e32 vcc, s4, v88
	v_cndmask_b32_e64 v1, 0, 1, s[6:7]
	s_nop 0
	v_cndmask_b32_e64 v35, 4, 0, vcc
	v_cmp_lt_i32_e32 vcc, s4, v90
	v_or_b32_e32 v34, v35, v34
	s_nop 0
	v_cndmask_b32_e64 v36, 8, 0, vcc
	v_cmp_ge_i32_e32 vcc, s4, v140
	s_and_b64 s[6:7], s[0:1], vcc
	v_cmp_lt_i32_e32 vcc, s4, v142
	v_or3_b32 v1, v34, v36, v1
	v_cndmask_b32_e64 v147, 0, v1, s[2:3]
	v_cndmask_b32_e64 v34, 2, 0, vcc
	v_cmp_lt_i32_e32 vcc, s4, v144
	v_cndmask_b32_e64 v1, 0, 1, s[6:7]
	s_cmpk_gt_i32 s4, 0xff
	v_cndmask_b32_e64 v35, 4, 0, vcc
	v_cmp_lt_i32_e32 vcc, s4, v146
	v_or_b32_e32 v34, v35, v34
	s_nop 0
	v_cndmask_b32_e64 v36, 8, 0, vcc
	v_or3_b32 v1, v34, v36, v1
	v_cndmask_b32_e64 v91, 0, v1, s[0:1]
	s_cbranch_scc0 .LBB0_1050
	v_and_b32_e32 v1, 1, v147
	s_waitcnt vmcnt(8)
	v_max_f32_e32 v34, v30, v30
	v_min_f32_e32 v35, 0x7f800000, v34
	v_max_f32_e32 v34, 0xff800000, v34
	v_cmp_eq_u32_e64 s[62:63], 1, v1
	v_max_f32_e32 v36, v31, v31
	v_cmp_gt_u32_e64 s[90:91], 8, v91
	v_cndmask_b32_e64 v1, v162, v34, s[62:63]
	v_cndmask_b32_e64 v34, v163, v35, s[62:63]
	v_and_b32_e32 v35, 2, v147
	v_min_f32_e32 v37, v34, v36
	v_max_f32_e32 v36, v1, v36
	v_cmp_eq_u32_e64 s[4:5], 0, v35
	v_cmp_ne_u32_e64 s[70:71], 0, v35
	v_and_b32_e32 v35, 4, v147
	v_cndmask_b32_e64 v1, v36, v1, s[4:5]
	v_writelane_b32 v252, s4, 41
	v_max_f32_e32 v36, v32, v32
	v_cmp_ne_u32_e64 s[66:67], 0, v35
	v_cndmask_b32_e64 v34, v37, v34, s[4:5]
	v_writelane_b32 v252, s5, 42
	v_min_f32_e32 v37, v34, v36
	v_max_f32_e32 v36, v1, v36
	v_cmp_eq_u32_e64 s[4:5], 0, v35
	v_max_f32_e32 v35, v33, v33
	v_cmp_lt_u32_e64 s[64:65], 7, v147
	v_cndmask_b32_e64 v1, v36, v1, s[4:5]
	v_writelane_b32 v252, s4, 43
	v_cmp_lt_u32_e64 s[52:53], 7, v139
	v_cmp_lt_u32_e64 s[36:37], 7, v131
	v_cndmask_b32_e64 v34, v37, v34, s[4:5]
	v_writelane_b32 v252, s5, 44
	v_min_f32_e32 v36, v34, v35
	v_max_f32_e32 v35, v1, v35
	v_cmp_gt_u32_e64 s[4:5], 8, v147
	v_cmp_lt_u32_e64 s[24:25], 7, v123
	v_cmp_lt_u32_e64 s[60:61], 7, v115
	v_cndmask_b32_e64 v1, v35, v1, s[4:5]
	v_writelane_b32 v252, s4, 45
	v_and_b32_e32 v35, 1, v139
	v_cmp_lt_u32_e64 s[42:43], 7, v107
	v_cndmask_b32_e64 v34, v36, v34, s[4:5]
	v_max_f32_e32 v36, v26, v26
	v_writelane_b32 v252, s5, 46
	v_min_f32_e32 v37, v34, v36
	v_max_f32_e32 v36, v1, v36
	v_cmp_eq_u32_e64 s[4:5], 1, v35
	v_and_b32_e32 v35, 2, v139
	v_cmp_ne_u32_e64 s[58:59], 0, v35
	v_cndmask_b32_e64 v1, v1, v36, s[4:5]
	v_writelane_b32 v252, s4, 47
	v_max_f32_e32 v38, v1, v1
	v_cmp_lt_u32_e64 s[18:19], 7, v99
	v_cndmask_b32_e64 v34, v34, v37, s[4:5]
	v_max_f32_e32 v36, v34, v34
	v_max_f32_e32 v37, v27, v27
	v_writelane_b32 v252, s5, 48
	v_min_f32_e32 v36, v36, v37
	v_max_f32_e32 v37, v38, v37
	v_cmp_eq_u32_e64 s[4:5], 0, v35
	v_and_b32_e32 v35, 4, v139
	v_cmp_ne_u32_e64 s[56:57], 0, v35
	v_cndmask_b32_e64 v1, v37, v1, s[4:5]
	v_writelane_b32 v252, s4, 49
	v_max_f32_e32 v37, v28, v28
	v_max_f32_e32 v38, v1, v1
	v_cndmask_b32_e64 v34, v36, v34, s[4:5]
	v_max_f32_e32 v36, v34, v34
	v_writelane_b32 v252, s5, 50
	v_min_f32_e32 v36, v36, v37
	v_max_f32_e32 v37, v38, v37
	v_cmp_eq_u32_e64 s[4:5], 0, v35
	s_nop 1
	v_cndmask_b32_e64 v1, v37, v1, s[4:5]
	v_writelane_b32 v252, s4, 51
	v_max_f32_e32 v37, v1, v1
	s_nop 0
	v_cndmask_b32_e64 v34, v36, v34, s[4:5]
	v_max_f32_e32 v35, v34, v34
	v_max_f32_e32 v36, v29, v29
	v_writelane_b32 v252, s5, 52
	v_min_f32_e32 v35, v35, v36
	v_max_f32_e32 v36, v37, v36
	v_cmp_gt_u32_e64 s[4:5], 8, v139
	v_max_f32_e32 v37, v22, v22
	s_nop 0
	v_cndmask_b32_e64 v1, v36, v1, s[4:5]
	v_writelane_b32 v252, s4, 53
	v_max_f32_e32 v38, v1, v1
	s_nop 0
	v_cndmask_b32_e64 v34, v35, v34, s[4:5]
	v_and_b32_e32 v35, 1, v131
	v_max_f32_e32 v36, v34, v34
	v_writelane_b32 v252, s5, 54
	v_min_f32_e32 v36, v36, v37
	v_max_f32_e32 v37, v38, v37
	v_cmp_eq_u32_e64 s[4:5], 1, v35
	v_and_b32_e32 v35, 2, v131
	v_cmp_ne_u32_e64 s[44:45], 0, v35
	v_cndmask_b32_e64 v1, v1, v37, s[4:5]
	v_writelane_b32 v252, s4, 55
	v_max_f32_e32 v37, v23, v23
	v_max_f32_e32 v38, v1, v1
	v_cndmask_b32_e64 v34, v34, v36, s[4:5]
	v_max_f32_e32 v36, v34, v34
	v_writelane_b32 v252, s5, 56
	v_min_f32_e32 v36, v36, v37
	v_max_f32_e32 v37, v38, v37
	v_cmp_eq_u32_e64 s[4:5], 0, v35
	v_and_b32_e32 v35, 4, v131
	v_cmp_ne_u32_e64 s[40:41], 0, v35
	v_cndmask_b32_e64 v1, v37, v1, s[4:5]
	v_writelane_b32 v252, s4, 57
	v_max_f32_e32 v37, v24, v24
	v_max_f32_e32 v38, v1, v1
	v_cndmask_b32_e64 v34, v36, v34, s[4:5]
	v_max_f32_e32 v36, v34, v34
	v_writelane_b32 v252, s5, 58
	v_min_f32_e32 v36, v36, v37
	v_max_f32_e32 v37, v38, v37
	v_cmp_eq_u32_e64 s[4:5], 0, v35
	s_nop 1
	v_cndmask_b32_e64 v1, v37, v1, s[4:5]
	v_writelane_b32 v252, s4, 59
	v_max_f32_e32 v37, v1, v1
	s_nop 0
	v_cndmask_b32_e64 v34, v36, v34, s[4:5]
	v_max_f32_e32 v35, v34, v34
	v_max_f32_e32 v36, v25, v25
	v_writelane_b32 v252, s5, 60
	v_min_f32_e32 v35, v35, v36
	v_max_f32_e32 v36, v37, v36
	v_cmp_gt_u32_e64 s[4:5], 8, v131
	v_max_f32_e32 v37, v18, v18
	s_nop 0
	v_cndmask_b32_e64 v1, v36, v1, s[4:5]
	v_writelane_b32 v252, s4, 61
	v_max_f32_e32 v38, v1, v1
	s_nop 0
	v_cndmask_b32_e64 v34, v35, v34, s[4:5]
	v_and_b32_e32 v35, 1, v123
	v_max_f32_e32 v36, v34, v34
	v_writelane_b32 v252, s5, 62
	v_min_f32_e32 v36, v36, v37
	v_max_f32_e32 v37, v38, v37
	v_cmp_eq_u32_e64 s[4:5], 1, v35
	v_and_b32_e32 v35, 2, v123
	v_cmp_ne_u32_e64 s[34:35], 0, v35
	v_cndmask_b32_e64 v1, v1, v37, s[4:5]
	v_writelane_b32 v252, s4, 63
	v_max_f32_e32 v37, v19, v19
	v_max_f32_e32 v38, v1, v1
	v_cndmask_b32_e64 v34, v34, v36, s[4:5]
	v_max_f32_e32 v36, v34, v34
	v_writelane_b32 v253, s5, 0
	v_min_f32_e32 v36, v36, v37
	v_max_f32_e32 v37, v38, v37
	v_cmp_eq_u32_e64 s[4:5], 0, v35
	v_and_b32_e32 v35, 4, v123
	v_cmp_ne_u32_e64 s[30:31], 0, v35
	v_cndmask_b32_e64 v1, v37, v1, s[4:5]
	v_writelane_b32 v253, s4, 1
	v_max_f32_e32 v37, v20, v20
	v_max_f32_e32 v38, v1, v1
	v_cndmask_b32_e64 v34, v36, v34, s[4:5]
	v_max_f32_e32 v36, v34, v34
	v_writelane_b32 v253, s5, 2
	v_min_f32_e32 v36, v36, v37
	v_max_f32_e32 v37, v38, v37
	v_cmp_eq_u32_e64 s[4:5], 0, v35
	s_nop 1
	v_cndmask_b32_e64 v1, v37, v1, s[4:5]
	v_writelane_b32 v253, s4, 3
	v_max_f32_e32 v37, v1, v1
	s_nop 0
	v_cndmask_b32_e64 v34, v36, v34, s[4:5]
	v_max_f32_e32 v35, v34, v34
	v_max_f32_e32 v36, v21, v21
	v_writelane_b32 v253, s5, 4
	v_min_f32_e32 v35, v35, v36
	v_max_f32_e32 v36, v37, v36
	v_cmp_gt_u32_e64 s[4:5], 8, v123
	v_max_f32_e32 v37, v14, v14
	s_nop 0
	v_cndmask_b32_e64 v1, v36, v1, s[4:5]
	v_writelane_b32 v253, s4, 5
	v_max_f32_e32 v38, v1, v1
	s_nop 0
	v_cndmask_b32_e64 v34, v35, v34, s[4:5]
	v_and_b32_e32 v35, 1, v115
	v_max_f32_e32 v36, v34, v34
	v_writelane_b32 v253, s5, 6
	v_min_f32_e32 v36, v36, v37
	v_max_f32_e32 v37, v38, v37
	v_cmp_eq_u32_e64 s[4:5], 1, v35
	v_and_b32_e32 v35, 2, v115
	v_cmp_ne_u32_e64 s[16:17], 0, v35
	v_cndmask_b32_e64 v1, v1, v37, s[4:5]
	v_writelane_b32 v253, s4, 7
	v_max_f32_e32 v37, v15, v15
	v_max_f32_e32 v38, v1, v1
	v_cndmask_b32_e64 v34, v34, v36, s[4:5]
	v_max_f32_e32 v36, v34, v34
	v_writelane_b32 v253, s5, 8
	v_min_f32_e32 v36, v36, v37
	v_max_f32_e32 v37, v38, v37
	v_cmp_eq_u32_e64 s[4:5], 0, v35
	v_and_b32_e32 v35, 4, v115
	v_cmp_ne_u32_e64 s[14:15], 0, v35
	v_cndmask_b32_e64 v1, v37, v1, s[4:5]
	v_writelane_b32 v253, s4, 9
	v_max_f32_e32 v37, v16, v16
	v_max_f32_e32 v38, v1, v1
	v_cndmask_b32_e64 v34, v36, v34, s[4:5]
	v_max_f32_e32 v36, v34, v34
	v_writelane_b32 v253, s5, 10
	v_min_f32_e32 v36, v36, v37
	v_max_f32_e32 v37, v38, v37
	v_cmp_eq_u32_e64 s[4:5], 0, v35
	s_nop 1
	v_cndmask_b32_e64 v1, v37, v1, s[4:5]
	v_writelane_b32 v253, s4, 11
	v_max_f32_e32 v37, v1, v1
	s_nop 0
	v_cndmask_b32_e64 v34, v36, v34, s[4:5]
	v_max_f32_e32 v35, v34, v34
	v_max_f32_e32 v36, v17, v17
	v_writelane_b32 v253, s5, 12
	v_min_f32_e32 v35, v35, v36
	v_max_f32_e32 v36, v37, v36
	v_cmp_gt_u32_e64 s[4:5], 8, v115
	v_max_f32_e32 v37, v10, v10
	s_nop 0
	v_cndmask_b32_e64 v1, v36, v1, s[4:5]
	v_writelane_b32 v252, s4, 2
	v_max_f32_e32 v38, v1, v1
	s_nop 0
	v_cndmask_b32_e64 v34, v35, v34, s[4:5]
	v_and_b32_e32 v35, 1, v107
	v_max_f32_e32 v36, v34, v34
	v_writelane_b32 v252, s5, 3
	v_min_f32_e32 v36, v36, v37
	v_max_f32_e32 v37, v38, v37
	v_cmp_eq_u32_e64 s[4:5], 1, v35
	s_nop 1
	v_cndmask_b32_e64 v1, v1, v37, s[4:5]
	v_writelane_b32 v253, s4, 13
	v_and_b32_e32 v37, 2, v107
	v_max_f32_e32 v38, v1, v1
	v_cndmask_b32_e64 v34, v34, v36, s[4:5]
	v_max_f32_e32 v35, v34, v34
	v_max_f32_e32 v36, v11, v11
	v_writelane_b32 v253, s5, 14
	v_min_f32_e32 v35, v35, v36
	v_max_f32_e32 v36, v38, v36
	v_cmp_eq_u32_e64 s[4:5], 0, v37
	v_and_b32_e32 v38, 4, v107
	v_cmp_ne_u32_e64 s[50:51], 0, v37
	v_cndmask_b32_e64 v1, v36, v1, s[4:5]
	v_writelane_b32 v252, s4, 0
	v_max_f32_e32 v36, v12, v12
	v_max_f32_e32 v39, v1, v1
	v_cndmask_b32_e64 v34, v35, v34, s[4:5]
	v_max_f32_e32 v35, v34, v34
	v_writelane_b32 v252, s5, 1
	v_min_f32_e32 v35, v35, v36
	v_max_f32_e32 v36, v39, v36
	v_cmp_eq_u32_e64 s[4:5], 0, v38
	v_cmp_ne_u32_e64 s[48:49], 0, v38
	s_nop 0
	v_cndmask_b32_e64 v1, v36, v1, s[4:5]
	v_writelane_b32 v251, s4, 62
	v_max_f32_e32 v36, v13, v13
	v_max_f32_e32 v39, v1, v1
	v_cndmask_b32_e64 v34, v35, v34, s[4:5]
	v_max_f32_e32 v35, v34, v34
	v_writelane_b32 v251, s5, 63
	v_min_f32_e32 v35, v35, v36
	v_max_f32_e32 v36, v39, v36
	v_cmp_gt_u32_e64 s[4:5], 8, v107
	v_max_f32_e32 v39, v6, v6
	s_nop 0
	v_cndmask_b32_e64 v1, v36, v1, s[4:5]
	v_writelane_b32 v252, s4, 10
	v_max_f32_e32 v40, v1, v1
	s_nop 0
	v_cndmask_b32_e64 v34, v35, v34, s[4:5]
	v_and_b32_e32 v35, 1, v99
	v_max_f32_e32 v36, v34, v34
	v_writelane_b32 v252, s5, 11
	v_min_f32_e32 v36, v36, v39
	v_max_f32_e32 v39, v40, v39
	v_cmp_eq_u32_e64 s[4:5], 1, v35
	s_nop 1
	v_cndmask_b32_e64 v1, v1, v39, s[4:5]
	v_writelane_b32 v253, s4, 15
	v_and_b32_e32 v39, 2, v99
	v_max_f32_e32 v40, v1, v1
	v_cndmask_b32_e64 v34, v34, v36, s[4:5]
	v_max_f32_e32 v35, v34, v34
	v_max_f32_e32 v36, v7, v7
	v_writelane_b32 v253, s5, 16
	v_min_f32_e32 v35, v35, v36
	v_max_f32_e32 v36, v40, v36
	v_cmp_eq_u32_e64 s[4:5], 0, v39
	v_and_b32_e32 v40, 4, v99
	v_cmp_ne_u32_e64 s[26:27], 0, v39
	v_cndmask_b32_e64 v1, v36, v1, s[4:5]
	v_writelane_b32 v252, s4, 8
	v_max_f32_e32 v36, v8, v8
	v_max_f32_e32 v41, v1, v1
	v_cndmask_b32_e64 v34, v35, v34, s[4:5]
	v_max_f32_e32 v35, v34, v34
	v_writelane_b32 v252, s5, 9
	v_min_f32_e32 v35, v35, v36
	v_max_f32_e32 v36, v41, v36
	v_cmp_eq_u32_e64 s[4:5], 0, v40
	v_cmp_ne_u32_e64 s[22:23], 0, v40
	s_nop 0
	v_cndmask_b32_e64 v1, v36, v1, s[4:5]
	v_writelane_b32 v252, s4, 6
	v_max_f32_e32 v36, v9, v9
	v_max_f32_e32 v41, v1, v1
	v_cndmask_b32_e64 v34, v35, v34, s[4:5]
	v_max_f32_e32 v35, v34, v34
	v_writelane_b32 v252, s5, 7
	v_min_f32_e32 v35, v35, v36
	v_max_f32_e32 v36, v41, v36
	v_cmp_gt_u32_e64 s[4:5], 8, v99
	v_max_f32_e32 v41, v2, v2
	s_nop 0
	v_cndmask_b32_e64 v1, v36, v1, s[4:5]
	v_writelane_b32 v252, s4, 4
	v_max_f32_e32 v42, v1, v1
	s_nop 0
	v_cndmask_b32_e64 v34, v35, v34, s[4:5]
	v_and_b32_e32 v35, 1, v91
	v_max_f32_e32 v36, v34, v34
	v_min_f32_e32 v36, v36, v41
	v_max_f32_e32 v41, v42, v41
	v_cmp_eq_u32_e64 s[94:95], 1, v35
	v_writelane_b32 v252, s5, 5
	s_nop 0
	v_cndmask_b32_e64 v1, v1, v41, s[94:95]
	v_cndmask_b32_e64 v34, v34, v36, s[94:95]
	v_and_b32_e32 v41, 2, v91
	v_max_f32_e32 v35, v34, v34
	v_max_f32_e32 v36, v3, v3
	v_max_f32_e32 v42, v1, v1
	v_min_f32_e32 v35, v35, v36
	v_max_f32_e32 v36, v42, v36
	v_cmp_eq_u32_e64 s[38:39], 0, v41
	v_and_b32_e32 v42, 4, v91
	v_cmp_eq_u32_e64 s[96:97], 0, v42
	v_cndmask_b32_e64 v1, v36, v1, s[38:39]
	v_cndmask_b32_e64 v34, v35, v34, s[38:39]
	v_max_f32_e32 v35, v34, v34
	v_max_f32_e32 v36, v4, v4
	v_max_f32_e32 v43, v1, v1
	v_min_f32_e32 v35, v35, v36
	v_max_f32_e32 v36, v43, v36
	v_cndmask_b32_e64 v1, v36, v1, s[96:97]
	v_cndmask_b32_e64 v34, v35, v34, s[96:97]
	v_max_f32_e32 v35, v34, v34
	v_max_f32_e32 v36, v5, v5
	v_max_f32_e32 v43, v1, v1
	v_min_f32_e32 v35, v35, v36
	v_max_f32_e32 v36, v43, v36
	v_cndmask_b32_e64 v1, v36, v1, s[90:91]
	v_cndmask_b32_e64 v34, v35, v34, s[90:91]
	v_cmp_ne_u32_e64 s[10:11], 0, v41
	v_mov_b32_dpp v35, v1 quad_perm:[1,0,3,2] row_mask:0xf bank_mask:0xf bound_ctrl:1
	v_max_f32_e32 v1, v1, v1
	v_max_f32_e32 v35, v35, v35
	v_max_f32_e32 v1, v1, v35
	v_cmp_ne_u32_e64 s[8:9], 0, v42
	s_nop 0
	v_mov_b32_dpp v35, v1 quad_perm:[2,3,0,1] row_mask:0xf bank_mask:0xf bound_ctrl:1
	v_max_f32_e32 v35, v35, v35
	v_max_f32_e32 v1, v1, v35
	s_nop 1
	v_mov_b32_dpp v35, v1 row_half_mirror row_mask:0xf bank_mask:0xf bound_ctrl:1
	v_max_f32_e32 v35, v35, v35
	v_max_f32_e32 v1, v1, v35
	s_nop 1
	v_mov_b32_dpp v35, v1 row_mirror row_mask:0xf bank_mask:0xf bound_ctrl:1
	v_max_f32_e32 v35, v35, v35
	v_max_f32_e32 v1, v1, v35
	s_nop 0
	v_readlane_b32 s6, v1, 48
	v_readlane_b32 s4, v1, 0
	v_readlane_b32 s5, v1, 16
	v_max_f32_e64 v35, s6, s6
	v_readlane_b32 s6, v1, 32
	s_nop 1
	v_max_f32_e64 v1, s6, s6
	v_max_f32_e32 v1, v1, v35
	v_mov_b32_e32 v35, s5
	v_max3_f32 v36, s4, v35, v1
	v_xor_b32_e32 v1, 0x80000000, v34
	v_max_f32_e64 v34, -v34, -v34
	v_mov_b32_e32 v35, 0
	v_mov_b32_dpp v1, v1 quad_perm:[1,0,3,2] row_mask:0xf bank_mask:0xf bound_ctrl:1
	v_max_f32_e32 v1, v1, v1
	v_max_f32_e32 v1, v34, v1
	s_nop 1
	v_mov_b32_dpp v34, v1 quad_perm:[2,3,0,1] row_mask:0xf bank_mask:0xf bound_ctrl:1
	v_max_f32_e32 v34, v34, v34
	v_max_f32_e32 v1, v1, v34
	s_nop 1
	v_mov_b32_dpp v34, v1 row_half_mirror row_mask:0xf bank_mask:0xf bound_ctrl:1
	v_max_f32_e32 v34, v34, v34
	v_max_f32_e32 v1, v1, v34
	s_nop 1
	v_mov_b32_dpp v34, v1 row_mirror row_mask:0xf bank_mask:0xf bound_ctrl:1
	v_max_f32_e32 v34, v34, v34
	v_max_f32_e32 v1, v1, v34
	s_nop 0
	v_readlane_b32 s6, v1, 48
	v_readlane_b32 s4, v1, 0
	v_readlane_b32 s5, v1, 16
	v_max_f32_e64 v34, s6, s6
	v_readlane_b32 s6, v1, 32
	s_nop 1
	v_max_f32_e64 v1, s6, s6
	v_max_f32_e32 v1, v1, v34
	v_mov_b32_e32 v34, s5
	v_max3_f32 v34, s4, v34, v1
	v_cmp_gt_f32_e64 s[4:5], v36, -v34
	s_and_b64 vcc, exec, s[4:5]
	v_mov_b32_e32 v1, 0
	v_cmp_lt_u32_e64 s[6:7], 7, v91
	s_cbranch_vccz .LBB0_740
	v_add_f32_e32 v35, v36, v34
	s_mov_b32 s12, 0x437ffd71
	v_div_scale_f32 v36, s[4:5], v35, v35, s12
	v_rcp_f32_e32 v37, v36
	v_div_scale_f32 v38, vcc, s12, v35, s12
	v_fma_f32 v39, -v36, v37, 1.0
	v_fmac_f32_e32 v37, v39, v37
	v_mul_f32_e32 v39, v38, v37
	v_fma_f32 v40, -v36, v39, v38
	v_fmac_f32_e32 v39, v40, v37
	v_fma_f32 v36, -v36, v39, v38
	v_div_fmas_f32 v36, v36, v37, v39
	v_div_fixup_f32 v35, v36, v35, s12
